# diff-attention mid-step: block B's first PV MFMA issued before the row-max check chain (wave-uniform branch test runs in the MFMA shadow; rare paths out of line)
# baseline (speedup 1.0000x reference)
.LstgV_skip:
	v_mfma_f32_32x32x16_bf16 v[48:63], v[160:163], v[144:147], v[48:63]
	ds_read_b64_tr_b16 v[180:181], v238 offset:8192
	ds_read_b64_tr_b16 v[182:183], v238 offset:8704
	v_exp_f32_e32 v249, v88
	v_exp_f32_e32 v250, v89
	v_add_f32_e32 v100, v247, v100
	v_add_f32_e32 v101, v248, v101
	v_mfma_f32_32x32x16_bf16 v[48:63], v[164:167], v[148:151], v[48:63]
	ds_read_b64_tr_b16 v[176:177], v238 offset:9216
	ds_read_b64_tr_b16 v[178:179], v238 offset:9728
	ds_read_b128 v[128:131], v96 offset:4096
	v_exp_f32_e32 v251, v90
	v_exp_f32_e32 v252, v91
	v_add_f32_e32 v100, v249, v100
	v_add_f32_e32 v101, v250, v101
	v_mfma_f32_32x32x16_bf16 v[16:31], v[160:163], v[152:155], v[16:31]
	ds_read_b64_tr_b16 v[172:173], v238 offset:12288
	ds_read_b64_tr_b16 v[174:175], v238 offset:12800
	v_exp_f32_e32 v253, v92
	v_exp_f32_e32 v239, v93
	v_add_f32_e32 v100, v251, v100
	v_add_f32_e32 v101, v252, v101
	v_mfma_f32_32x32x16_bf16 v[16:31], v[164:167], v[156:159], v[16:31]
	ds_read_b64_tr_b16 v[168:169], v238 offset:13312
	ds_read_b64_tr_b16 v[170:171], v238 offset:13824
	ds_read_b128 v[132:135], v97 offset:4096
	ds_read_b128 v[136:139], v98 offset:4096
	ds_read_b128 v[140:143], v99 offset:4096
	v_exp_f32_e32 v240, v94
	v_exp_f32_e32 v99, v95
	v_add_f32_e32 v100, v253, v100
	v_add_f32_e32 v101, v239, v101
	v_add_f32_e32 v100, v240, v100
	v_add_f32_e32 v101, v99, v101
	v_add_f32_e32 v100, v100, v101
	v_add_f32_e32 v235, v235, v100
	v_cvt_pk_bf16_f32 v156, v241, v242
	v_cvt_pk_bf16_f32 v157, v243, v244
	v_cvt_pk_bf16_f32 v158, v245, v246
	v_cvt_pk_bf16_f32 v159, v247, v248
	v_cvt_pk_bf16_f32 v162, v249, v250
	v_cvt_pk_bf16_f32 v163, v251, v252
	v_cvt_pk_bf16_f32 v164, v253, v239
	v_cvt_pk_bf16_f32 v165, v240, v99
	s_waitcnt lgkmcnt(7)
	v_mfma_f32_32x32x16_bf16 v[96:111], v[128:131], v[112:115], v[64:79]
	v_max3_f32 v144, v80, v81, v82
	v_max3_f32 v145, v83, v84, v85
	s_waitcnt lgkmcnt(2)
	v_mfma_f32_32x32x16_bf16 v[96:111], v[132:135], v[116:119], v[96:111]
	v_max3_f32 v128, v144, v86, v87
	v_max3_f32 v129, v145, v88, v89
	s_waitcnt lgkmcnt(1)
	v_mfma_f32_32x32x16_bf16 v[96:111], v[136:139], v[120:123], v[96:111]
	v_max3_f32 v128, v128, v90, v91
	v_max3_f32 v129, v129, v92, v93
	s_nop 0
	v_max3_f32 v128, v128, v94, v95
	s_waitcnt lgkmcnt(0)
	v_mfma_f32_32x32x16_bf16 v[96:111], v[140:143], v[124:127], v[96:111]
	v_max_f32_e32 v128, v128, v129
	ds_bpermute_b32 v129, v214, v128
	s_andn2_b64 vcc, exec, s[0:1]
	s_cbranch_vccz .LBB0_522
	s_and_b32 s20, s2, 0xc000
	s_add_i32 s20, s65, s20
	s_waitcnt lgkmcnt(1)
	v_mfma_f32_32x32x16_bf16 v[0:15], v[156:159], v[196:199], v[0:15]
	s_waitcnt lgkmcnt(0)
	v_max_f32_e32 v80, v128, v129
	v_cmp_lt_f32_e32 vcc, s67, v80
	s_cmp_lg_u64 vcc, 0
	s_cselect_b64 s[0:1], -1, 0
	s_cbranch_vccnz .LBB0_525b
.LafterB:
	ds_read_b64_tr_b16 v[128:129], v238 offset:2048
	ds_read_b64_tr_b16 v[130:131], v238 offset:2560
	v_exp_f32_e32 v160, v96
	v_exp_f32_e32 v161, v97
	v_add_u32_e32 v152, s20, v228
	v_add_u32_e32 v239, s20, v229
	v_add_u32_e32 v240, s20, v230
	v_mfma_f32_32x32x16_bf16 v[0:15], v[162:165], v[192:195], v[0:15]
	ds_read_b64_tr_b16 v[132:133], v238 offset:3072
	ds_read_b64_tr_b16 v[134:135], v238 offset:3584
	v_exp_f32_e32 v166, v98
	v_exp_f32_e32 v167, v99
	v_mfma_f32_32x32x16_bf16 v[32:47], v[156:159], v[188:191], v[32:47]
	ds_read_b64_tr_b16 v[136:137], v238 offset:6144
	ds_read_b64_tr_b16 v[138:139], v238 offset:6656
	v_exp_f32_e32 v192, v100
	v_exp_f32_e32 v193, v101
	v_mfma_f32_32x32x16_bf16 v[32:47], v[162:165], v[184:187], v[32:47]
	ds_read_b64_tr_b16 v[140:141], v238 offset:7168
	ds_read_b64_tr_b16 v[142:143], v238 offset:7680
	v_exp_f32_e32 v188, v102
	v_exp_f32_e32 v189, v103
	v_mfma_f32_32x32x16_bf16 v[48:63], v[156:159], v[180:183], v[48:63]
	ds_read_b64_tr_b16 v[144:145], v238 offset:10240
	ds_read_b64_tr_b16 v[146:147], v238 offset:10752
	v_exp_f32_e32 v184, v104
	v_exp_f32_e32 v185, v105
	v_mfma_f32_32x32x16_bf16 v[48:63], v[162:165], v[176:179], v[48:63]
	ds_read_b64_tr_b16 v[148:149], v238 offset:11264
	ds_read_b64_tr_b16 v[150:151], v238 offset:11776
	ds_read_b128 v[180:183], v152
	v_exp_f32_e32 v186, v106
	v_exp_f32_e32 v187, v107
	v_mfma_f32_32x32x16_bf16 v[16:31], v[156:159], v[172:175], v[16:31]
	ds_read_b64_tr_b16 v[152:153], v238 offset:14336
	ds_read_b64_tr_b16 v[154:155], v238 offset:14848
	v_exp_f32_e32 v176, v108
	v_exp_f32_e32 v177, v109
	v_mfma_f32_32x32x16_bf16 v[16:31], v[162:165], v[168:171], v[16:31]
	ds_read_b64_tr_b16 v[156:157], v238 offset:15360
	ds_read_b64_tr_b16 v[158:159], v238 offset:15872
	v_add_f32_e32 v162, v166, v160
	v_add_f32_e32 v163, v167, v161
	v_exp_f32_e32 v178, v110
	v_exp_f32_e32 v179, v111
	v_pk_add_f32 v[164:165], v[192:193], v[162:163]
	ds_read_b128 v[168:171], v239
	ds_read_b128 v[172:175], v240
	v_pk_add_f32 v[164:165], v[188:189], v[164:165]
	v_cvt_pk_bf16_f32 v160, v160, v161
	v_cvt_pk_bf16_f32 v161, v166, v167
	v_pk_add_f32 v[166:167], v[184:185], v[164:165]
	v_cvt_pk_bf16_f32 v162, v192, v193
	v_pk_add_f32 v[166:167], v[186:187], v[166:167]
	v_cvt_pk_bf16_f32 v163, v188, v189
	v_cvt_pk_bf16_f32 v164, v184, v185
	v_cvt_pk_bf16_f32 v165, v186, v187
	v_pk_add_f32 v[184:185], v[176:177], v[166:167]
	v_cvt_pk_bf16_f32 v166, v176, v177
	v_cvt_pk_bf16_f32 v167, v178, v179
	v_pk_add_f32 v[176:177], v[178:179], v[184:185]
	s_waitcnt lgkmcnt(6)
	v_mfma_f32_32x32x16_bf16 v[80:95], v[180:183], v[112:115], v[64:79]
	v_max3_f32 v178, v96, v97, v98
	v_add_f32_e32 v96, v176, v177
	v_add_f32_e32 v235, v235, v96
	v_add_u32_e32 v96, s20, v231
	v_max3_f32 v100, v99, v100, v101
	ds_read_b128 v[96:99], v96
	s_waitcnt lgkmcnt(2)
	v_mfma_f32_32x32x16_bf16 v[80:95], v[168:171], v[116:119], v[80:95]
	v_max3_f32 v101, v178, v102, v103
	v_max3_f32 v100, v100, v104, v105
	s_waitcnt lgkmcnt(1)
	v_mfma_f32_32x32x16_bf16 v[80:95], v[172:175], v[120:123], v[80:95]
	v_max3_f32 v101, v101, v106, v107
	v_max3_f32 v100, v100, v108, v109
	s_nop 0
	v_max3_f32 v101, v101, v110, v111
	v_max_f32_e32 v100, v101, v100
	s_waitcnt lgkmcnt(0)
	v_mfma_f32_32x32x16_bf16 v[80:95], v[96:99], v[124:127], v[80:95]
	ds_bpermute_b32 v101, v214, v100
	s_addk_i32 s2, 0x4000
	s_add_i32 s3, s3, -1
	s_cmp_ge_u32 s37, s84
	s_cbranch_scc1 .LBB0_527
	s_mov_b32 s76, s37
	s_branch .LBB0_502

.LBB0_512:
	s_and_b32 s20, s2, 0xc000
	s_add_i32 s20, s65, s20
	v_mfma_f32_32x32x16_bf16 v[0:15], v[156:159], v[196:199], v[0:15]
	s_branch .LafterB
.LBB0_525b:
	v_max_f32_e32 v64, v80, v80
	v_max_f32_e32 v64, 0, v64
	v_exp_f32_e64 v232, -v64
	v_add_f32_e32 v233, v233, v64
	v_xor_b32_e32 v80, 0x80000000, v233
	v_sub_f32_e32 v111, v111, v64
	v_sub_f32_e32 v110, v110, v64
	v_sub_f32_e32 v109, v109, v64
	v_sub_f32_e32 v108, v108, v64
	v_sub_f32_e32 v107, v107, v64
	v_sub_f32_e32 v106, v106, v64
	v_sub_f32_e32 v105, v105, v64
	v_sub_f32_e32 v104, v104, v64
	v_sub_f32_e32 v103, v103, v64
	v_sub_f32_e32 v102, v102, v64
	v_sub_f32_e32 v101, v101, v64
	v_sub_f32_e32 v100, v100, v64
	v_sub_f32_e32 v99, v99, v64
	v_sub_f32_e32 v98, v98, v64
	v_sub_f32_e32 v97, v97, v64
	v_sub_f32_e32 v96, v96, v64
	v_mul_f32_e32 v235, v235, v232
	v_mov_b32_e32 v64, v80
	v_mov_b32_e32 v65, v80
	v_mov_b32_e32 v66, v80
	v_mov_b32_e32 v67, v80
	v_mov_b32_e32 v68, v80
	v_mov_b32_e32 v69, v80
	v_mov_b32_e32 v70, v80
	v_mov_b32_e32 v71, v80
	v_mov_b32_e32 v72, v80
	v_mov_b32_e32 v73, v80
	v_mov_b32_e32 v74, v80
	v_mov_b32_e32 v75, v80
	v_mov_b32_e32 v76, v80
	v_mov_b32_e32 v77, v80
	v_mov_b32_e32 v78, v80
	v_mov_b32_e32 v79, v80
	s_branch .LafterB
.Lhd_w0:
	s_waitcnt vmcnt(0)
	s_branch .Lhd_bar
